# hand 3 in-projection tiles of the 32 longest workgroups to idle ones; shortconv hoisted weights, single wait per task, carried by the waves without a GLA task
# speedup vs baseline: 1.0120x; 1.0036x over previous
; __device__ __forceinline__ int otid() { int t = threadIdx.x; asm volatile("" : "+v"(t)); return t; }
; __device__ __forceinline__ unsigned xb_ld(unsigned* p)              { return __hip_atomic_load(p, __ATOMIC_RELAXED, __HIP_MEMORY_SCOPE_AGENT); }
; #define WSP asglobal(p->ws)
; __device__ __forceinline__ void xcd_barrier_complete(unsigned* bar, unsigned x, unsigned& nloc, unsigned& nx) {
;     const unsigned G = gridDim.x * gridDim.y * gridDim.z;
;     unsigned sum, cnt, mine, sp = 0u;
;     for (;;) {
;         sum = 0u; cnt = 0u; mine = 0u;
; #pragma unroll
;         for (unsigned j = 0; j < 16; ++j) { const unsigned c = xb_ld(&bar[XB_XCNT(j)]); sum += c; cnt += (c > 0u) ? 1u : 0u; mine = (j == x) ? c : mine; }
;         if (sum == G) break;
;         __builtin_amdgcn_s_sleep(1);
;         if ((++sp & 255u) == 0u) { if (xb_ld(&bar[XB_TMO])) break; if (sp > XB_SPIN_CAP) { atomicAdd(&bar[XB_TMO], 1u); break; } }
;     }
;     nloc = mine > 0u ? mine : 1u; nx = cnt > 0u ? cnt : 1u;
; }
; __device__ __forceinline__ void vt_phase(ParamsK p, unsigned char* smem) {
;     const bf16_t* U = (const bf16_t*)(WSP + WS_U);
;     bf16_t* tile = (bf16_t*)smem;
;     constexpr int TS = 72, NITEM = (TT / 64) * 12;
;     const int tid = otid();
;     const int tok = tid >> 3, d8 = (tid & 7) * 8;
;     auto src = [&](int item) { const int tt = item / 12, hs = item % 12; const int col0 = hs < 6 ? NV0 + hs * 64 : V0 + (hs - 6) * 64;
;         return U + (size_t)(tt * 64 + tok) * INP + col0 + d8; };
;     int item = blockIdx.x;
;     u32x4 wn = (u32x4){0u, 0u, 0u, 0u};
;     if (item < NITEM) wn = *(const u32x4*)src(item);
.LBB0_149:
	s_or_b64 exec, exec, s[2:3]
	s_ashr_i32 s31, s70, 31
	s_lshl_b32 s20, s70, 4
	s_add_u32 s22, s16, 0x3a6d8200
	s_addc_u32 s23, s17, 0
	s_add_u32 s24, s16, 0x3a6d8400
	s_addc_u32 s25, s17, 0
	s_add_u32 s26, s16, 0x3a6d8500
	s_addc_u32 s27, s17, 0
	s_waitcnt lgkmcnt(0)
	s_add_u32 s0, s16, 0x3a6d8600
	s_addc_u32 s1, s17, 0
	v_writelane_b32 v252, s0, 7
	v_cvt_f32_u32_e32 v0, s70
	s_mul_i32 s71, s71, s70
	v_writelane_b32 v252, s1, 8
	s_add_u32 s0, s16, 0x3a6d8700
	s_addc_u32 s1, s17, 0
	v_writelane_b32 v252, s0, 9
	v_rcp_iflag_f32_e32 v0, v0
	s_mul_i32 s12, s71, s33
	v_writelane_b32 v252, s1, 10
	s_add_u32 s0, s16, 0x3a6d8800
	s_addc_u32 s1, s17, 0
	v_writelane_b32 v252, s0, 11
	v_mul_f32_e32 v0, 0x4f7ffffe, v0
	v_cvt_u32_f32_e32 v0, v0
	v_writelane_b32 v252, s1, 12
	s_add_u32 s0, s16, 0x3a6d8900
	s_addc_u32 s1, s17, 0
	v_writelane_b32 v252, s0, 13
	v_mov_b32_e32 v1, 0
	v_mov_b32_e32 v162, 0x358637bd
	v_writelane_b32 v252, s1, 14
	s_add_u32 s0, s16, 0x3a6d8a00
	s_addc_u32 s1, s17, 0
	v_writelane_b32 v252, s0, 15
	v_mov_b32_e32 v229, 1
	v_mov_b64_e32 v[164:165], 0x6e8
	v_writelane_b32 v252, s1, 16
	s_add_u32 s0, s16, 0x3a6d8b00
	s_addc_u32 s1, s17, 0
	v_writelane_b32 v252, s0, 17
	v_mov_b64_e32 v[166:167], 0x6e7
	v_mov_b64_e32 v[168:169], 0xd68
	v_writelane_b32 v252, s1, 18
	s_add_u32 s0, s16, 0x3a6d8c00
	s_addc_u32 s1, s17, 0
	v_writelane_b32 v252, s0, 19
	v_mov_b64_e32 v[170:171], 0xd67
	v_mov_b32_e32 v230, 0x41b17218
	v_writelane_b32 v252, s1, 20
	s_add_u32 s0, s16, 0x3a6d8d00
	s_addc_u32 s1, s17, 0
	v_writelane_b32 v252, s0, 21
	v_mov_b32_e32 v231, 0x4200
	v_mov_b32_e32 v232, 0x6300
	v_writelane_b32 v252, s1, 22
	s_add_u32 s0, s16, 0x3a6d8e00
	s_addc_u32 s1, s17, 0
	v_writelane_b32 v252, s0, 23
	v_mov_b32_e32 v233, 0xff
	v_mov_b32_e32 v234, 0x1fff
	v_writelane_b32 v252, s1, 24
	s_add_u32 s0, s16, 0x3a6d8f00
	s_addc_u32 s1, s17, 0
	v_writelane_b32 v252, s0, 25
	v_mov_b32_e32 v235, 0xe0
	v_mov_b32_e32 v236, 0x1fe0
	v_writelane_b32 v252, s1, 26
	s_add_u32 s0, s16, 0x3a6d9000
	s_addc_u32 s1, s17, 0
	v_writelane_b32 v252, s0, 27
	v_mov_b64_e32 v[172:173], 0x680
	v_mov_b64_e32 v[174:175], 0x67f
	v_writelane_b32 v252, s1, 28
	s_add_u32 s0, s16, 0x3a6d9100
	s_addc_u32 s1, s17, 0
	v_writelane_b32 v252, s0, 29
	s_mov_b32 s33, 0x10000
	s_movk_i32 s80, 0x2000
	v_writelane_b32 v252, s1, 30
	s_add_u32 s0, s16, 0x3a6d9200
	s_addc_u32 s1, s17, 0
	s_add_u32 s14, s16, 0x3a6d9300
	s_addc_u32 s15, s17, 0
	v_writelane_b32 v252, s0, 31
	s_cmp_eq_u32 s50, 15
	s_movk_i32 s81, 0x1600
	v_writelane_b32 v252, s1, 32
	s_cselect_b64 s[0:1], -1, 0
	v_writelane_b32 v252, s0, 33
	s_cmp_eq_u32 s50, 14
	s_mov_b32 s82, 0x800000
	v_writelane_b32 v252, s1, 34
	s_cselect_b64 s[0:1], -1, 0
	v_writelane_b32 v252, s0, 35
	s_cmp_eq_u32 s50, 13
	s_movk_i32 s83, 0x1a00
	v_writelane_b32 v252, s1, 36
	s_cselect_b64 s[0:1], -1, 0
	v_writelane_b32 v252, s0, 37
	s_cmp_eq_u32 s50, 12
	s_movk_i32 s84, 0x300
	v_writelane_b32 v252, s1, 38
	s_cselect_b64 s[0:1], -1, 0
	v_writelane_b32 v252, s0, 39
	s_cmp_eq_u32 s50, 11
	s_movk_i32 s85, 0x58
	v_writelane_b32 v252, s1, 40
	s_cselect_b64 s[0:1], -1, 0
	v_writelane_b32 v252, s0, 41
	s_cmp_eq_u32 s50, 10
	s_movk_i32 s86, 0x1000
	v_writelane_b32 v252, s1, 42
	s_cselect_b64 s[0:1], -1, 0
	v_writelane_b32 v252, s0, 43
	s_cmp_eq_u32 s50, 9
	s_movk_i32 s87, 0x50
	v_writelane_b32 v252, s1, 44
	s_cselect_b64 s[0:1], -1, 0
	v_writelane_b32 v252, s0, 45
	s_cmp_eq_u32 s50, 8
	s_movk_i32 s88, 0x310
	v_writelane_b32 v252, s1, 46
	s_cselect_b64 s[0:1], -1, 0
	v_writelane_b32 v252, s0, 47
	s_cmp_eq_u32 s50, 7
	s_mov_b32 s89, 0xbfb8aa3b
	v_writelane_b32 v252, s1, 48
	s_cselect_b64 s[0:1], -1, 0
	v_writelane_b32 v252, s0, 49
	s_cmp_eq_u32 s50, 6
	s_mov_b32 s90, 0x3f317217
	v_writelane_b32 v252, s1, 50
	s_cselect_b64 s[0:1], -1, 0
	v_writelane_b32 v252, s0, 51
	s_cmp_eq_u32 s50, 5
	s_mov_b32 s91, 0x7f800000
	v_writelane_b32 v252, s1, 52
	s_cselect_b64 s[0:1], -1, 0
	v_writelane_b32 v252, s0, 53
	s_cmp_eq_u32 s50, 4
	s_movk_i32 s92, 0x2c00
	v_writelane_b32 v252, s1, 54
	s_cselect_b64 s[0:1], -1, 0
	v_writelane_b32 v252, s0, 55
	s_cmp_eq_u32 s50, 3
	s_mov_b32 s30, 0x3db8aa3b
	v_writelane_b32 v252, s1, 56
	s_cselect_b64 s[0:1], -1, 0
	v_writelane_b32 v252, s0, 57
	s_cmp_eq_u32 s50, 2
	s_mov_b32 s36, 0x3e38aa3b
	v_writelane_b32 v252, s1, 58
	s_cselect_b64 s[0:1], -1, 0
	v_writelane_b32 v252, s0, 59
	s_cmp_eq_u32 s50, 1
	s_nop 0
	v_writelane_b32 v252, s1, 60
	s_cselect_b64 s[0:1], -1, 0
	v_writelane_b32 v252, s0, 61
	s_cmp_eq_u32 s50, 0
	s_nop 0
	v_writelane_b32 v252, s1, 62
	s_cselect_b64 s[0:1], -1, 0
	v_writelane_b32 v252, s0, 63
	s_nop 0
	v_readlane_b32 s10, v252, 0
	v_writelane_b32 v251, s1, 0
	s_lshl_b32 s0, s50, 8
	s_add_u32 s0, s18, s0
	s_addc_u32 s1, s19, 0
	s_add_u32 s2, s0, 0x1400
	s_addc_u32 s3, s1, 0
	v_writelane_b32 v251, s2, 1
	s_add_u32 s0, s0, 0x2400
	s_addc_u32 s1, s1, 0
	v_writelane_b32 v251, s3, 2
	v_writelane_b32 v251, s0, 3
	s_nop 1
	v_writelane_b32 v251, s1, 4
	s_add_u32 s0, s16, 0x3a6db400
	s_addc_u32 s1, s17, 0
	v_writelane_b32 v251, s0, 5
	s_nop 1
	v_writelane_b32 v251, s1, 6
	s_add_u32 s0, s16, 0x3a6db500
	s_addc_u32 s1, s17, 0
	v_writelane_b32 v251, s0, 7
	s_cmpk_lt_i32 s10, 0x3180
	s_nop 0
	v_writelane_b32 v251, s1, 8
	s_cselect_b64 s[0:1], -1, 0
	v_writelane_b32 v251, s0, 9
	s_nop 1
	v_writelane_b32 v251, s1, 10
	s_mul_hi_i32 s0, s10, 0x2aaaaaab
	s_lshr_b32 s1, s0, 31
	s_ashr_i32 s0, s0, 1
	s_add_i32 s0, s0, s1
	s_mul_i32 s1, s0, 12
	s_sub_i32 s1, s10, s1
	s_lshl_b32 s2, s1, 6
	s_add_i32 s3, s2, 0xaa0
	s_cmp_lt_i32 s1, 6
	s_cselect_b32 s18, s3, s2
	s_lshl_b32 s0, s0, 6
	v_writelane_b32 v251, s0, 11
	s_and_b32 s1, s10, -8
;     __host__ __device__ bool next(int i, Unit& u) const {
;         const long L = (long)i * G + c; if (L >= nwg) return false;
;         int wgid = (int)L; { const int q = nwg / NXCD, r = nwg % NXCD, xcd = wgid % NXCD, off = wgid / NXCD; wgid = (xcd < r ? xcd * (q + 1) : r * (q + 1) + (xcd - r) * q) + off; }
;         const int nig = WGM * nN, gid = wgid / nig, fm = gid * WGM, gsz = (nM - fm) < WGM ? (nM - fm) : WGM;
;         u.pm = fm + ((wgid % nig) % gsz); u.pn = (wgid % nig) / gsz; return true;
; __device__ __forceinline__ void shortconv_phase(ParamsK p, int l) {
;     ...
;     const int NGW = gridDim.x * 8, gw = wave * gridDim.x + blockIdx.x;
;     const int extra = (48 * NCH) % NGW;
;     const bool subset = (NGW - extra) * 2 >= NGW && extra > 0;
;     if (subset && gw < extra) return;
;     const int gt = subset ? (gw - extra) * 64 + lane : gw * 64 + lane, NGT = subset ? (NGW - extra) * 64 : NGW * 64;
	s_and_b32 s0, s10, 7
	v_writelane_b32 v251, s1, 12
	s_and_b32 s1, s70, -8
	s_cmpk_lg_i32 s1, 0x100
	v_writelane_b32 v251, s1, 13
	s_cselect_b64 s[2:3], -1, 0
	v_writelane_b32 v251, s2, 14
	s_sub_i32 s1, 0, s70
	s_lshl_b32 s4, s0, 13
	v_writelane_b32 v251, s3, 15
	v_readfirstlane_b32 s2, v0
	s_mul_i32 s1, s1, s2
	s_mul_hi_u32 s1, s2, s1
	s_add_i32 s1, s2, s1
	s_mul_hi_u32 s2, s10, s1
	s_mul_i32 s2, s2, s70
	s_lshl_b32 s3, s0, 8
	v_writelane_b32 v251, s4, 16
	s_sub_i32 s2, s10, s2
	v_writelane_b32 v251, s3, 17
	s_bitset1_b32 s3, 16
	v_writelane_b32 v251, s3, 18
	s_add_i32 s8, s10, 0xe0
	s_sub_i32 s3, s2, s70
	s_cmp_ge_u32 s2, s70
	s_cselect_b32 s2, s3, s2
	s_sub_i32 s3, s2, s70
	s_cmp_ge_u32 s2, s70
	s_cselect_b32 s17, s3, s2
	s_cmpk_lt_i32 s17, 0x6e8
	s_cselect_b64 s[2:3], -1, 0
	v_writelane_b32 v251, s2, 19
	s_ashr_i32 s37, s17, 31
	s_mul_hi_u32 s1, s8, s1
	v_writelane_b32 v251, s3, 20
	s_lshr_b32 s2, s37, 29
	s_add_i32 s2, s17, s2
	s_ashr_i32 s7, s2, 3
	s_and_b32 s2, s2, -8
	s_sub_i32 s11, s17, s2
	s_cmp_lt_i32 s11, 0
	s_cselect_b64 s[2:3], -1, 0
	v_writelane_b32 v251, s2, 21
	s_mul_i32 s1, s1, s70
	s_mul_i32 s0, s0, 6
	v_writelane_b32 v251, s3, 22
	s_and_b64 s[2:3], s[2:3], exec
	s_movk_i32 s2, 0xde
	s_cselect_b32 s2, s2, 0xdd
	s_mul_i32 s2, s11, s2
	s_movk_i32 s3, 0x1ae
	s_cselect_b32 s4, s3, 0x1ad
	s_add_i32 s2, s2, s7
	s_mul_hi_i32 s3, s2, 0x4ec4ec4f
	s_lshr_b32 s5, s3, 31
	s_ashr_i32 s3, s3, 5
	s_add_i32 s3, s3, s5
	s_mul_i32 s5, s3, 0x68
	s_sub_i32 s2, s2, s5
	s_bfe_i32 s5, s2, 0x80000
	s_bfe_u32 s5, s5, 0x3000c
	s_add_i32 s5, s2, s5
	s_and_b32 s6, s5, 0xf8
	s_sub_i32 s2, s2, s6
	s_bfe_i32 s5, s5, 0x80000
	s_lshl_b32 s3, s3, 3
	s_sext_i32_i16 s5, s5
	s_sext_i32_i8 s2, s2
	s_add_i32 s28, s3, s2
	s_ashr_i32 s2, s5, 3
	v_writelane_b32 v251, s2, 23
	s_lshr_b32 s2, s5, 3
	s_bfe_i64 s[2:3], s[2:3], 0x100000
	s_lshl_b64 s[2:3], s[2:3], 19
	v_writelane_b32 v251, s2, 24
	s_ashr_i32 s29, s28, 31
	s_nop 0
	v_writelane_b32 v251, s3, 25
	s_mov_b32 s2, s28
	v_writelane_b32 v251, s2, 26
	s_nop 1
	v_writelane_b32 v251, s3, 27
	s_lshl_b64 s[2:3], s[28:29], 19
	v_writelane_b32 v251, s2, 28
	s_cmpk_lt_i32 s17, 0xd68
	s_nop 0
	v_writelane_b32 v251, s3, 29
	s_mul_i32 s2, s4, s11
	s_cselect_b64 s[4:5], -1, 0
	s_add_i32 s2, s2, s7
	v_writelane_b32 v251, s4, 30
	s_mul_hi_i32 s3, s2, 0x4ec4ec4f
	s_nop 0
	v_writelane_b32 v251, s5, 31
	s_lshr_b32 s4, s3, 31
	s_ashr_i32 s3, s3, 5
	s_add_i32 s3, s3, s4
	s_mul_i32 s4, s3, 0x68
	s_sub_i32 s2, s2, s4
	s_bfe_i32 s4, s2, 0x80000
	s_bfe_u32 s4, s4, 0x3000c
	s_add_i32 s4, s2, s4
	s_and_b32 s5, s4, 0xf8
	s_sub_i32 s2, s2, s5
	s_abs_i32 s5, s62
	v_cvt_f32_u32_e32 v0, s5
	s_bfe_i32 s4, s4, 0x80000
	s_lshl_b32 s3, s3, 3
	s_sext_i32_i16 s4, s4
	v_rcp_iflag_f32_e32 v0, v0
	s_sext_i32_i8 s2, s2
	v_writelane_b32 v251, s7, 32
	s_add_i32 s28, s3, s2
	v_mul_f32_e32 v0, 0x4f7ffffe, v0
	v_cvt_u32_f32_e32 v0, v0
	s_ashr_i32 s2, s4, 3
	s_sub_i32 s6, 0, s5
	v_writelane_b32 v251, s2, 33
	v_readfirstlane_b32 s7, v0
	s_lshr_b32 s2, s4, 3
	s_mul_i32 s6, s6, s7
	s_bfe_i64 s[2:3], s[2:3], 0x100000
	s_mul_hi_u32 s6, s7, s6
	s_lshl_b64 s[2:3], s[2:3], 19
	s_add_i32 s7, s7, s6
	v_writelane_b32 v251, s2, 34
	s_ashr_i32 s29, s28, 31
	s_mov_b32 s4, s28
	v_writelane_b32 v251, s3, 35
	s_mul_hi_u32 s2, s7, 0x630
	s_mul_i32 s2, s2, s5
	s_sub_i32 s2, 0x630, s2
	s_sub_i32 s3, s2, s5
	s_lshl_b64 s[6:7], s[28:29], 19
	v_writelane_b32 v251, s4, 36
	s_cmp_ge_u32 s2, s5
	s_cselect_b32 s2, s3, s2
	s_sub_i32 s3, s2, s5
	s_cmp_ge_u32 s2, s5
	s_cselect_b32 s16, s3, s2
	s_sub_i32 s9, s62, s16
	v_writelane_b32 v251, s5, 37
	s_lshl_b32 s4, s9, 1
	s_cmp_lg_u32 s16, 0
	s_cselect_b64 s[2:3], -1, 0
	s_cmp_eq_u32 s62, s62
	v_writelane_b32 v251, s6, 38
	s_cselect_b64 s[4:5], -1, 0
	v_mbcnt_lo_u32_b32 v0, -1, 0
	v_writelane_b32 v251, s7, 39
	s_and_b64 s[6:7], s[4:5], exec
	v_writelane_b32 v251, s16, 40
	s_cselect_b32 s16, s16, 0
	v_writelane_b32 v251, s16, 41
	s_and_b64 s[2:3], s[2:3], s[4:5]
	s_lshl_b32 s4, s9, 6
	v_writelane_b32 v251, s2, 42
	s_mov_b64 s[6:7], s[24:25]
	v_mbcnt_hi_u32_b32 v228, -1, v0
	v_writelane_b32 v251, s3, 43
	s_and_b64 s[2:3], s[2:3], exec
	s_mov_b32 s2, s56
	v_writelane_b32 v251, s2, 44
	s_cselect_b32 s5, s4, s56
	s_sub_i32 s1, s8, s1
	v_writelane_b32 v251, s3, 45
	v_writelane_b32 v251, s11, 46
	s_lshr_b32 s2, s11, 31
	v_writelane_b32 v251, s2, 47
	s_sub_i32 s2, s1, s70
	s_cmp_ge_u32 s1, s70
	s_cselect_b32 s1, s2, s1
	s_sub_i32 s2, s1, s70
	s_cmp_ge_u32 s1, s70
	s_cselect_b32 s73, s2, s1
	s_cmpk_lt_i32 s73, 0x680
	s_cselect_b64 s[2:3], -1, 0
	s_ashr_i32 s77, s73, 31
	s_lshr_b32 s1, s77, 29
	v_writelane_b32 v251, s2, 48
	s_add_i32 s1, s73, s1
	s_mov_b64 s[8:9], s[22:23]
	v_writelane_b32 v251, s3, 49
	s_ashr_i32 s2, s1, 3
	s_and_b32 s1, s1, -8
	s_sub_i32 s1, s73, s1
	s_cmp_lt_i32 s1, 0
	s_movk_i32 s3, 0xd1
	s_cselect_b32 s3, s3, 0xd0
	s_mul_i32 s1, s1, s3
	s_add_i32 s1, s1, s2
	s_mul_hi_i32 s2, s1, 0x4ec4ec4f
	s_lshr_b32 s3, s2, 31
	s_ashr_i32 s2, s2, 5
	s_add_i32 s2, s2, s3
	s_mul_i32 s3, s2, 0x68
	s_sub_i32 s1, s1, s3
	s_bfe_i32 s3, s1, 0x80000
	s_bfe_u32 s3, s3, 0x3000c
	s_add_i32 s3, s1, s3
	s_and_b32 s4, s3, 0xf8
	s_sub_i32 s4, s1, s4
	s_mov_b32 s1, 0
	s_mov_b32 s19, s1
	v_writelane_b32 v251, s18, 50
	s_ashr_i32 s21, s20, 31
	s_mov_b64 s[28:29], 0x80
	v_writelane_b32 v251, s19, 51
	v_writelane_b32 v251, s0, 52
	s_lshl_b32 s0, s2, 3
	s_bfe_i32 s2, s3, 0x80000
	s_sext_i32_i16 s2, s2
	s_sext_i32_i8 s3, s4
	s_add_i32 s18, s0, s3
	s_ashr_i32 s0, s2, 3
	v_writelane_b32 v251, s0, 53
	s_lshr_b32 s0, s2, 3
	s_bfe_i64 s[2:3], s[0:1], 0x100000
	s_lshl_b64 s[2:3], s[2:3], 19
	v_writelane_b32 v251, s2, 54
	s_lshl_b32 s0, s10, 4
	s_and_b32 s0, s0, 0xffffff80
	v_writelane_b32 v251, s3, 55
	v_writelane_b32 v251, s0, 56
	v_readlane_b32 s0, v252, 1
	s_add_i32 s0, s0, s62
	s_ashr_i32 s19, s18, 31
	v_writelane_b32 v251, s0, 57
	s_and_b32 s0, s20, 0xffffff80
	v_writelane_b32 v251, s0, 58
	v_writelane_b32 v251, s5, 59
	s_lshl_b32 s0, s5, 3
	v_writelane_b32 v251, s0, 60
	s_mov_b32 s0, s18
	v_writelane_b32 v251, s0, 61
	s_lshl_b64 s[2:3], s[18:19], 19
	s_mov_b64 s[10:11], s[26:27]
	v_writelane_b32 v251, s1, 62
	v_writelane_b32 v251, s2, 63
	s_mov_b32 s16, 0x3e3504f3
	s_mov_b32 s0, s1
	v_writelane_b32 v250, s3, 0
	v_writelane_b32 v250, s20, 1
	s_lshl_b64 s[2:3], s[20:21], 11
	s_nop 0
	v_writelane_b32 v250, s21, 2
	v_writelane_b32 v250, s2, 3
	s_nop 1
	v_writelane_b32 v250, s3, 4
	s_mov_b64 s[2:3], 0
	v_writelane_b32 v250, s2, 5
	s_nop 1
	v_writelane_b32 v250, s3, 6
	v_writelane_b32 v250, s8, 7
	s_nop 1
	v_writelane_b32 v250, s9, 8
	v_writelane_b32 v250, s6, 9
	s_nop 1
	v_writelane_b32 v250, s7, 10
	v_writelane_b32 v250, s10, 11
	s_nop 1
	v_writelane_b32 v250, s11, 12
	v_writelane_b32 v250, s96, 13
	s_nop 1
	v_writelane_b32 v250, s97, 14
	v_writelane_b32 v250, s73, 15
	v_writelane_b32 v250, s77, 16
	s_branch .LBB0_152

; __device__ __forceinline__ int otid() { int t = threadIdx.x; asm volatile("" : "+v"(t)); return t; }
; #define IN(i) asglobal(p->in[i])
; #define WSP asglobal(p->ws)
; __device__ __forceinline__ void shortconv_phase(ParamsK p, int l) {
;     const bf16_t* U = (const bf16_t*)(WSP + WS_U); bf16_t* MIX = (bf16_t*)(WSP + WS_H);
;     const float* cw = IN(14) + (size_t)l * 3 * 256; const float* cbias = IN(15) + (size_t)l * 256;
;     const int tid = otid(), lane = tid & 63, wave = __builtin_amdgcn_readfirstlane(tid >> 6);
;     const int NGW = gridDim.x * 8, gw = wave * gridDim.x + blockIdx.x;
;     const int extra = (48 * NCH) % NGW;
;     const bool subset = (NGW - extra) * 2 >= NGW && extra > 0;
;     if (subset && gw < extra) return;
;     const int gt = subset ? (gw - extra) * 64 + lane : gw * 64 + lane, NGT = subset ? (NGW - extra) * 64 : NGW * 64;
;     for (int task = gt; task < TT * 32; task += NGT) {
;         const int R = task >> 5, c = (task & 31) * 8;
;         int pos, L; if (R < TL) { pos = R & (SEQ - 1); L = SEQ; } else { pos = (R - TL) & (CTXL - 1); L = CTXL; }
;         const bf16_t* ur = U + (size_t)R * INP;
;         float bgt[8], cc[8], xx[8], acc[8];
;         unpack8(*(const u32x4*)(ur + SB0 + c), bgt);
;         unpack8(*(const u32x4*)(ur + SC0 + c), cc); unpack8(*(const u32x4*)(ur + SX0 + c), xx);
; #pragma unroll
;         for (int i = 0; i < 8; ++i) acc[i] = cbias[c + i] + cw[256 + c + i] * (cc[i] * xx[i]);
.LBB0_839:
	v_readlane_b32 s96, v250, 13
	v_readlane_b32 s97, v250, 14
	s_mov_b64 s[22:23], s[96:97]
	v_mov_b32_e32 v0, v163
	v_readlane_b32 s2, v252, 0
	v_readfirstlane_b32 s0, v0
	s_ashr_i32 s0, s0, 6
	s_mul_i32 s0, s0, s70
	s_add_i32 s0, s0, s2
	v_readlane_b32 s2, v251, 40
	s_cmp_lt_i32 s0, s2
	v_readlane_b32 s4, v251, 42
	s_cselect_b64 s[2:3], -1, 0
	v_readlane_b32 s5, v251, 43
	s_and_b64 s[2:3], s[4:5], s[2:3]
	v_readlane_b32 s94, v252, 4
	s_andn2_b64 vcc, exec, s[2:3]
	v_readlane_b32 s95, v252, 5
	v_readlane_b32 s73, v250, 15
	v_readlane_b32 s77, v250, 16
	s_cbranch_vccz .LBB0_848
	v_readlane_b32 s2, v251, 41
	v_and_b32_e32 v0, 63, v0
	s_sub_i32 s0, s0, s2
	v_lshl_or_b32 v22, s0, 6, v0
	s_mov_b32 s2, 0x210000
	v_cmp_gt_i32_e32 vcc, s2, v22
	s_and_saveexec_b64 s[18:19], vcc
	s_cbranch_execz .LBB0_847
	s_load_dwordx2 s[20:21], s[22:23], 0xc0
	s_load_dwordx4 s[4:7], s[22:23], 0x70
	v_readlane_b32 s26, v250, 19
	s_mul_i32 s3, s26, 0xc00
	v_readlane_b32 s27, v250, 20
	s_waitcnt lgkmcnt(0)
	s_add_u32 s22, s20, 0xf1d8000
	s_addc_u32 s23, s21, 0
	s_mul_hi_u32 s2, s26, 0xc00
	s_add_u32 s24, s4, s3
	s_addc_u32 s25, s5, s2
	s_lshl_b64 s[2:3], s[26:27], 10
	s_add_u32 s26, s6, s2
	s_addc_u32 s27, s7, s3
	v_readlane_b32 s6, v250, 9
	v_lshlrev_b32_e32 v0, 3, v0
	v_readlane_b32 s7, v250, 10
	v_lshl_or_b32 v23, s0, 9, v0
	v_and_b32_e32 v52, 0xf8, v23
	v_lshlrev_b32_e32 v52, 2, v52
	global_load_dwordx4 v[176:179], v52, s[26:27] offset:16
	global_load_dwordx4 v[180:183], v52, s[26:27]
	global_load_dwordx4 v[184:187], v52, s[24:25] offset:1040
	global_load_dwordx4 v[188:191], v52, s[24:25] offset:1024
	global_load_dwordx4 v[192:195], v52, s[24:25] offset:16
	global_load_dwordx4 v[196:199], v52, s[24:25]
	global_load_dwordx4 v[200:203], v52, s[24:25] offset:2064
	global_load_dwordx4 v[204:207], v52, s[24:25] offset:2048
	s_mov_b64 s[38:39], 0
	s_branch .LBB0_843

; __device__ __forceinline__ unsigned pk2(float lo, float hi) { return pg8::cvt_pk_bf16(lo, hi); }
; __device__ __forceinline__ void shortconv_phase(ParamsK p, int l) {
;     ...
;     for (int task = gt; task < TT * 32; task += NGT) {
;         const int R = task >> 5, c = (task & 31) * 8;
;         int pos, L; if (R < TL) { pos = R & (SEQ - 1); L = SEQ; } else { pos = (R - TL) & (CTXL - 1); L = CTXL; }
;         const bf16_t* ur = U + (size_t)R * INP;
;         float bgt[8], cc[8], xx[8], acc[8];
;         unpack8(*(const u32x4*)(ur + SB0 + c), bgt);
;         unpack8(*(const u32x4*)(ur + SC0 + c), cc); unpack8(*(const u32x4*)(ur + SX0 + c), xx);
; #pragma unroll
;         for (int i = 0; i < 8; ++i) acc[i] = cbias[c + i] + cw[256 + c + i] * (cc[i] * xx[i]);
;         if (pos > 0) { unpack8(*(const u32x4*)(ur - INP + SC0 + c), cc); unpack8(*(const u32x4*)(ur - INP + SX0 + c), xx);
; #pragma unroll
;             for (int i = 0; i < 8; ++i) acc[i] += cw[c + i] * (cc[i] * xx[i]); }
;         if (pos < L - 1) { unpack8(*(const u32x4*)(ur + INP + SC0 + c), cc); unpack8(*(const u32x4*)(ur + INP + SX0 + c), xx);
; #pragma unroll
;             for (int i = 0; i < 8; ++i) acc[i] += cw[512 + c + i] * (cc[i] * xx[i]); }
;         u32x4 w; w.x = pk2(bgt[0] * acc[0], bgt[1] * acc[1]); w.y = pk2(bgt[2] * acc[2], bgt[3] * acc[3]); w.z = pk2(bgt[4] * acc[4], bgt[5] * acc[5]); w.w = pk2(bgt[6] * acc[6], bgt[7] * acc[7]);
;         *(u32x4*)(MIX + (size_t)R * DM + 384 + c) = w;
.LBB0_843:
	v_ashrrev_i32_e32 v6, 5, v22
	v_and_b32_e32 v8, 0xf8, v23
	v_mov_b64_e32 v[2:3], s[22:23]
	v_mad_i64_i32 v[14:15], s[2:3], v6, s83, v[2:3]
	v_lshlrev_b32_e32 v0, 1, v8
	v_lshl_add_u64 v[20:21], v[14:15], 0, v[0:1]
	global_load_dwordx4 v[2:5], v[20:21], off offset:2368
	global_load_dwordx4 v[16:19], v[20:21], off offset:2880
	global_load_dwordx4 v[26:29], v[20:21], off offset:3392
	v_cmp_gt_i32_e32 vcc, s33, v6
	v_lshl_add_u64 v[14:15], v[14:15], 0, v[0:1]
	s_nop 0
	v_cndmask_b32_e32 v7, v233, v234, vcc
	v_and_b32_e32 v24, v7, v6
	v_add_co_u32_e32 v14, vcc, 0x2000, v14
	s_nop 1
	v_addc_co_u32_e32 v15, vcc, 0, v15, vcc
	v_cmp_ne_u32_e32 vcc, 0, v24
	s_and_saveexec_b64 s[40:41], vcc
	global_load_dwordx4 v[208:211], v[20:21], off offset:-3776
	global_load_dwordx4 v[212:215], v[20:21], off offset:-3264
	s_or_b64 exec, exec, s[40:41]
	v_cmp_ne_u32_e32 vcc, v24, v7
	s_and_saveexec_b64 s[40:41], vcc
	global_load_dwordx4 v[216:219], v[14:15], off offset:1344
	global_load_dwordx4 v[220:223], v[14:15], off offset:1856
	s_or_b64 exec, exec, s[40:41]
	s_waitcnt vmcnt(0)
	v_lshlrev_b32_e32 v12, 16, v16
	v_and_b32_e32 v13, 0xffff0000, v16
	v_lshlrev_b32_e32 v50, 16, v26
	v_and_b32_e32 v51, 0xffff0000, v26
	v_pk_mul_f32 v[8:9], v[12:13], v[50:51]
	v_lshlrev_b32_e32 v12, 16, v17
	v_and_b32_e32 v13, 0xffff0000, v17
	v_lshlrev_b32_e32 v16, 16, v27
	v_and_b32_e32 v17, 0xffff0000, v27
	v_lshlrev_b32_e32 v46, 16, v19
	v_lshlrev_b32_e32 v48, 16, v29
	v_pk_mul_f32 v[12:13], v[12:13], v[16:17]
	v_lshlrev_b32_e32 v16, 16, v18
	v_and_b32_e32 v17, 0xffff0000, v18
	v_lshlrev_b32_e32 v26, 16, v28
	v_and_b32_e32 v27, 0xffff0000, v28
	v_and_b32_e32 v49, 0xffff0000, v29
	v_and_b32_e32 v47, 0xffff0000, v19
	v_pk_mul_f32 v[16:17], v[16:17], v[26:27]
	v_pk_mul_f32 v[18:19], v[46:47], v[48:49]
	v_pk_fma_f32 v[8:9], v[188:189], v[8:9], v[180:181]
	v_pk_fma_f32 v[12:13], v[12:13], v[190:191], v[182:183]
	v_pk_fma_f32 v[16:17], v[16:17], v[184:185], v[176:177]
	v_pk_fma_f32 v[18:19], v[18:19], v[186:187], v[178:179]
	v_cmp_ne_u32_e32 vcc, 0, v24
	s_and_saveexec_b64 s[40:41], vcc
	s_cbranch_execz .Lscp_a
	v_lshlrev_b32_e32 v44, 16, v208
	v_and_b32_e32 v45, 0xffff0000, v208
	v_lshlrev_b32_e32 v46, 16, v212
	v_and_b32_e32 v47, 0xffff0000, v212
	v_lshlrev_b32_e32 v208, 16, v209
	v_and_b32_e32 v209, 0xffff0000, v209
	v_lshlrev_b32_e32 v212, 16, v213
	v_and_b32_e32 v213, 0xffff0000, v213
	v_lshlrev_b32_e32 v42, 16, v211
	v_lshlrev_b32_e32 v20, 16, v215
	v_pk_mul_f32 v[44:45], v[44:45], v[46:47]
	v_pk_mul_f32 v[208:209], v[208:209], v[212:213]
	v_lshlrev_b32_e32 v212, 16, v210
	v_and_b32_e32 v213, 0xffff0000, v210
	v_lshlrev_b32_e32 v46, 16, v214
	v_and_b32_e32 v47, 0xffff0000, v214
	v_and_b32_e32 v21, 0xffff0000, v215
	v_and_b32_e32 v43, 0xffff0000, v211
	v_pk_mul_f32 v[212:213], v[212:213], v[46:47]
	v_pk_mul_f32 v[20:21], v[42:43], v[20:21]
	v_pk_fma_f32 v[8:9], v[196:197], v[44:45], v[8:9]
	v_pk_fma_f32 v[12:13], v[198:199], v[208:209], v[12:13]
	v_pk_fma_f32 v[16:17], v[212:213], v[192:193], v[16:17]
	v_pk_fma_f32 v[18:19], v[20:21], v[194:195], v[18:19]
.Lscp_a:
	s_or_b64 exec, exec, s[40:41]
	v_cmp_ne_u32_e32 vcc, v24, v7
	s_and_saveexec_b64 s[40:41], vcc
	s_cbranch_execz .LBB0_842
	v_lshlrev_b32_e32 v40, 16, v216
	v_and_b32_e32 v41, 0xffff0000, v216
	v_lshlrev_b32_e32 v42, 16, v220
	v_and_b32_e32 v43, 0xffff0000, v220
	v_lshlrev_b32_e32 v216, 16, v217
	v_and_b32_e32 v217, 0xffff0000, v217
	v_lshlrev_b32_e32 v220, 16, v221
	v_and_b32_e32 v221, 0xffff0000, v221
	v_lshlrev_b32_e32 v20, 16, v219
	v_lshlrev_b32_e32 v14, 16, v223
	v_pk_mul_f32 v[10:11], v[40:41], v[42:43]
	v_pk_mul_f32 v[216:217], v[216:217], v[220:221]
	v_lshlrev_b32_e32 v220, 16, v218
	v_and_b32_e32 v221, 0xffff0000, v218
	v_lshlrev_b32_e32 v40, 16, v222
	v_and_b32_e32 v41, 0xffff0000, v222
	v_and_b32_e32 v15, 0xffff0000, v223
	v_and_b32_e32 v21, 0xffff0000, v219
	v_pk_mul_f32 v[220:221], v[220:221], v[40:41]
	v_pk_mul_f32 v[14:15], v[20:21], v[14:15]
	v_pk_fma_f32 v[12:13], v[206:207], v[216:217], v[12:13]
	v_pk_fma_f32 v[18:19], v[14:15], v[202:203], v[18:19]
	v_pk_fma_f32 v[16:17], v[220:221], v[200:201], v[16:17]
	v_pk_fma_f32 v[8:9], v[204:205], v[10:11], v[8:9]
	s_branch .LBB0_842

;     __host__ __device__ bool next(int i, Unit& u) const {
;         const long L = (long)i * G + c; if (L >= nwg) return false;
;         int wgid = (int)L; { const int q = nwg / NXCD, r = nwg % NXCD, xcd = wgid % NXCD, off = wgid / NXCD; wgid = (xcd < r ? xcd * (q + 1) : r * (q + 1) + (xcd - r) * q) + off; }
;         const int nig = WGM * nN, gid = wgid / nig, fm = gid * WGM, gsz = (nM - fm) < WGM ? (nM - fm) : WGM;
;         u.pm = fm + ((wgid % nig) % gsz); u.pn = (wgid % nig) / gsz; return true;
.LBB0_1272:
	s_add_i32 s56, s56, 1
	s_mul_i32 s10, s56, s31
	s_mul_hi_u32 s11, s56, s70
	s_add_i32 s11, s11, s10
	s_mul_i32 s10, s56, s70
	s_add_u32 s34, s10, s73
	s_addc_u32 s35, s11, s77
	s_cmp_lt_u32 s73, 224
	s_cbranch_scc1 .Lrb6_a
	s_cmp_lt_u32 s56, 3
	s_cbranch_scc1 .Lrb6_done
	s_mov_b32 s34, 0x7fffffff
	s_mov_b32 s35, 0
	s_branch .Lrb6_done
.Lrb6_a:
	s_cmp_lt_u32 s73, 128
	s_cbranch_scc1 .Lrb6_done
	s_cmp_ge_u32 s73, 224
	s_cbranch_scc1 .Lrb6_done
	s_cmp_lg_u32 s56, 6
	s_cbranch_scc1 .Lrb6_done
	s_sub_i32 s10, s73, 128
	s_lshr_b32 s11, s10, 5
	s_and_b32 s10, s10, 31
	s_add_i32 s11, s11, 3
	s_lshl_b32 s11, s11, 8
	s_add_i32 s34, s11, s10
	s_addk_i32 s34, 0xe0
	s_mov_b32 s35, 0
